# P1 modulate loop: all row/gain/shift/scale loads of an iteration issued up front (hoisted into spare VGPRs, counted vmcnt waits), on top of the new barrier
# baseline (speedup 1.0000x reference)
; #define GAS __attribute__((address_space(1)))
; DI unsigned pk2(float a, float b) { f32x2 v = {a, b}; bf16x2_t r = __builtin_convertvector(v, bf16x2_t); return __builtin_bit_cast(unsigned, r); }
; DI float bflo(unsigned u) { return __uint_as_float(u << 16); }
; DI float bfhi(unsigned u) { return __uint_as_float(u & 0xffff0000u); }
; template <bool LAT_BF16>
; DI void modulate_phase(const float* xlat, const float* xctx, const float* g, const float* mods_l, bf16_t* h, int tid) {
;     ...
;     for (int row0 = gw; row0 < MTOT; row0 += 2 * ngw) {
;         const float* src[2]; const float* md[2]; int row[2]; bool ok[2];
;         f32x4 v[2][4];
; #pragma unroll
;         for (int q = 0; q < 2; ++q) {
;             row[q] = row0 + q * ngw; ok[q] = row[q] < MTOT;
;             const int rr = ok[q] ? row[q] : row0;
;             if (rr < MLAT) { src[q] = xlat + (size_t)rr * D; md[q] = mods_l + (rr >> 13) * 3072; }
;             else { src[q] = xctx + (size_t)(rr - MLAT) * D; md[q] = mods_l + 2 * 3072; }
; #pragma unroll
;             for (int j = 0; j < 4; ++j) {
;                 if (LAT_BF16 && rr < MLAT) {
;                     const u32x2 b2 = *(const GAS u32x2*)((const bf16_t*)xlat + (size_t)rr * D + lane * 4 + 256 * j);
;                     v[q][j] = (f32x4){bflo(b2.x), bfhi(b2.x), bflo(b2.y), bfhi(b2.y)};
;                 } else v[q][j] = *(const GAS f32x4*)(src[q] + lane * 4 + 256 * j);
;             }
;         }
; #pragma unroll
;         for (int q = 0; q < 2; ++q) {
;             float ss = 0.f;
; #pragma unroll
;             for (int j = 0; j < 4; ++j) ss += (v[q][j].x * v[q][j].x + v[q][j].y * v[q][j].y) + (v[q][j].z * v[q][j].z + v[q][j].w * v[q][j].w);
;             const float rstd = 1.f / sqrtf(wave_sum(ss) * (1.f / D) + EPS);
;             if (ok[q]) {
; #pragma unroll
;                 for (int j = 0; j < 4; ++j) {
;                     const int k = lane * 4 + 256 * j;
;                     const f32x4 gg = *(const GAS f32x4*)(g + k), sh = *(const GAS f32x4*)(md[q] + k), sc = *(const GAS f32x4*)(md[q] + 1024 + k);
;                     const f32x4 o = (v[q][j] * rstd * gg) * (sc + 1.f) + sh;
;                     u32x2 w; w.x = pk2(o.x, o.y); w.y = pk2(o.z, o.w);
;                     *(GAS u32x2*)(h + (size_t)row[q] * D + k) = w;
.LBB0_129:
	s_waitcnt lgkmcnt(0)
	v_mov_b64_e32 v[4:5], v[2:3]
	v_cmp_lt_i32_e32 vcc, s18, v71
	v_mov_b64_e32 v[2:3], v[0:1]
	s_and_saveexec_b64 s[6:7], vcc
	s_xor_b64 s[6:7], exec, s[6:7]
	v_add_u32_e32 v38, 0xffffc000, v71
	v_lshlrev_b64 v[2:3], 12, v[38:39]
	v_lshl_add_u64 v[2:3], s[56:57], 0, v[2:3]
	s_or_saveexec_b64 s[6:7], s[6:7]
	v_mov_b64_e32 v[10:11], s[14:15]
	s_xor_b64 exec, exec, s[6:7]
	v_ashrrev_i32_e32 v4, 13, v71
	v_mul_i32_i24_e32 v4, 0xc00, v4
	v_ashrrev_i32_e32 v5, 31, v4
	v_lshl_add_u64 v[10:11], v[4:5], 2, s[12:13]
	s_or_b64 exec, exec, s[6:7]
	v_lshlrev_b32_e32 v38, 2, v36
	v_lshl_add_u64 v[2:3], v[2:3], 0, v[38:39]
	global_load_dwordx4 v[30:33], v[2:3], off
	global_load_dwordx4 v[26:29], v[2:3], off offset:1024
	global_load_dwordx4 v[22:25], v[2:3], off offset:2048
	s_nop 0
	global_load_dwordx4 v[2:5], v[2:3], off offset:3072
	v_add_u32_e32 v56, s3, v71
	v_cmp_gt_i32_e64 s[6:7], s1, v56
	s_nop 1
	v_cndmask_b32_e64 v12, v71, v56, s[6:7]
	v_cmp_lt_i32_e32 vcc, s18, v12
	s_and_saveexec_b64 s[8:9], vcc
	s_xor_b64 s[8:9], exec, s[8:9]
	v_add_u32_e32 v6, 0xffffc000, v12
	v_mov_b32_e32 v7, v39
	v_lshlrev_b64 v[6:7], 12, v[6:7]
	v_lshl_add_u64 v[8:9], s[56:57], 0, v[6:7]
	s_or_saveexec_b64 s[8:9], s[8:9]
	v_mov_b64_e32 v[58:59], s[14:15]
	s_xor_b64 exec, exec, s[8:9]
	v_ashrrev_i32_e32 v13, 31, v12
	v_lshlrev_b64 v[6:7], 12, v[12:13]
	v_lshl_add_u64 v[8:9], s[52:53], 0, v[6:7]
	v_ashrrev_i32_e32 v6, 13, v12
	v_mul_i32_i24_e32 v6, 0xc00, v6
	v_ashrrev_i32_e32 v7, 31, v6
	v_lshl_add_u64 v[58:59], v[6:7], 2, s[12:13]
	s_or_b64 exec, exec, s[8:9]
	v_lshl_add_u64 v[84:85], v[10:11], 0, s[44:45]
	v_lshl_add_u64 v[86:87], v[10:11], 0, v[38:39]
	global_load_dwordx4 v[72:75], v[40:41], off
	v_lshl_add_u64 v[10:11], v[84:85], 0, v[38:39]
	global_load_dwordx4 v[76:79], v[86:87], off
	global_load_dwordx4 v[80:83], v[10:11], off
	v_lshl_add_u64 v[96:97], v[8:9], 0, v[38:39]
	global_load_dwordx4 v[100:103], v[96:97], off
	v_lshl_add_u64 v[98:99], v[8:9], 0, v[38:39]
	global_load_dwordx4 v[104:107], v[98:99], off offset:1024
	v_lshl_add_u64 v[108:109], v[8:9], 0, v[38:39]
	global_load_dwordx4 v[112:115], v[108:109], off offset:2048
	v_lshl_add_u64 v[110:111], v[8:9], 0, v[38:39]
	global_load_dwordx4 v[116:119], v[110:111], off offset:3072
	global_load_dwordx4 v[120:123], v[40:41], off offset:1024
	v_lshlrev_b32_e32 v124, 2, v42
	v_mov_b32_e32 v125, v39
	v_lshl_add_u64 v[126:127], v[84:85], 0, v[124:125]
	global_load_dwordx4 v[128:131], v[126:127], off
	global_load_dwordx4 v[132:135], v[86:87], off offset:1024
	global_load_dwordx4 v[136:139], v[40:41], off offset:2048
	v_lshlrev_b32_e32 v140, 2, v44
	v_mov_b32_e32 v141, v39
	v_lshl_add_u64 v[142:143], v[84:85], 0, v[140:141]
	global_load_dwordx4 v[144:147], v[142:143], off
	global_load_dwordx4 v[148:151], v[86:87], off offset:2048
	global_load_dwordx4 v[152:155], v[40:41], off offset:3072
	v_lshlrev_b32_e32 v156, 2, v46
	v_mov_b32_e32 v157, v39
	v_lshl_add_u64 v[158:159], v[84:85], 0, v[156:157]
	global_load_dwordx4 v[160:163], v[158:159], off
	global_load_dwordx4 v[164:167], v[86:87], off offset:3072
	s_waitcnt vmcnt(19)
	v_pk_mul_f32 v[6:7], v[32:33], v[32:33]
	v_pk_mul_f32 v[12:13], v[30:31], v[30:31]
	s_nop 0
	v_pk_mov_b32 v[14:15], v[12:13], v[6:7] op_sel:[1,0]
	v_mov_b32_e32 v13, v7
	v_pk_add_f32 v[6:7], v[14:15], v[12:13]
	s_waitcnt vmcnt(18)
	v_pk_mul_f32 v[12:13], v[28:29], v[28:29]
	v_pk_mul_f32 v[14:15], v[26:27], v[26:27]
	v_pk_add_f32 v[6:7], v[6:7], v[6:7] op_sel:[0,1] op_sel_hi:[1,0]
	v_pk_mov_b32 v[16:17], v[14:15], v[12:13] op_sel:[1,0]
	v_mov_b32_e32 v15, v13
	v_pk_add_f32 v[12:13], v[16:17], v[14:15]
	s_waitcnt vmcnt(16)
	v_mul_f32_e32 v14, v2, v2
	v_mul_f32_e32 v15, v3, v3
	v_pk_add_f32 v[12:13], v[12:13], v[12:13] op_sel:[0,1] op_sel_hi:[1,0]
	v_mov_b32_e32 v7, v14
	v_mov_b32_e32 v13, v15
	v_pk_add_f32 v[6:7], v[6:7], v[12:13]
	v_mul_f32_e32 v12, v23, v23
	v_mul_f32_e32 v14, v25, v25
	v_mul_f32_e32 v16, v4, v4
	v_mul_f32_e32 v17, v5, v5
	v_pk_fma_f32 v[12:13], v[22:23], v[22:23], v[12:13] op_sel_hi:[1,1,0]
	v_pk_fma_f32 v[14:15], v[24:25], v[24:25], v[14:15] op_sel_hi:[1,1,0]
	v_mov_b32_e32 v13, v16
	v_mov_b32_e32 v15, v17
	v_pk_add_f32 v[12:13], v[12:13], v[14:15]
	s_nop 0
	v_pk_add_f32 v[6:7], v[6:7], v[12:13]
	s_nop 0
	v_add_f32_e32 v6, v6, v7
	ds_bpermute_b32 v7, v65, v6
	s_waitcnt lgkmcnt(0)
	v_add_f32_e32 v6, v6, v7
	ds_bpermute_b32 v7, v66, v6
	s_waitcnt lgkmcnt(0)
	v_add_f32_e32 v6, v6, v7
	ds_bpermute_b32 v7, v67, v6
	s_waitcnt lgkmcnt(0)
	v_add_f32_e32 v6, v6, v7
	ds_bpermute_b32 v7, v68, v6
	s_waitcnt lgkmcnt(0)
	v_add_f32_e32 v6, v6, v7
	ds_bpermute_b32 v7, v69, v6
	s_waitcnt lgkmcnt(0)
	v_add_f32_e32 v6, v6, v7
	ds_bpermute_b32 v7, v70, v6
	s_waitcnt lgkmcnt(0)
	v_add_f32_e32 v6, v6, v7
	v_fmamk_f32 v6, v6, 0x3a800000, v35
	v_mul_f32_e32 v7, 0x4f800000, v6
	v_cmp_gt_f32_e32 vcc, s19, v6
	s_nop 1
	v_cndmask_b32_e32 v10, v6, v7, vcc
	v_sqrt_f32_e32 v11, v10
	v_lshl_add_u64 v[6:7], v[8:9], 0, v[38:39]
	v_add_u32_e32 v8, -1, v11
	v_fma_f32 v9, -v8, v11, v10
	v_cmp_ge_f32_e64 s[8:9], 0, v9
	v_add_u32_e32 v9, 1, v11
	s_nop 0
	v_cndmask_b32_e64 v8, v11, v8, s[8:9]
	v_fma_f32 v11, -v9, v11, v10
	v_cmp_lt_f32_e64 s[8:9], 0, v11
	s_nop 1
	v_cndmask_b32_e64 v8, v8, v9, s[8:9]
	v_mul_f32_e32 v9, 0x37800000, v8
	v_cndmask_b32_e32 v8, v8, v9, vcc
	v_cmp_class_f32_e32 vcc, v10, v37
	s_nop 1
	v_cndmask_b32_e32 v57, v8, v10, vcc
	v_div_scale_f32 v88, s[8:9], v57, v57, 1.0
	v_rcp_f32_e32 v89, v88
	s_nop 0
	v_fma_f32 v90, -v88, v89, 1.0
	v_fmac_f32_e32 v89, v90, v89
	v_div_scale_f32 v90, vcc, 1.0, v57, 1.0
	v_mul_f32_e32 v91, v90, v89
	v_fma_f32 v92, -v88, v91, v90
	v_fmac_f32_e32 v91, v92, v89
	v_fma_f32 v88, -v88, v91, v90
	v_div_fmas_f32 v88, v88, v89, v91
	v_div_fixup_f32 v88, v88, v57, 1.0
	v_pk_mul_f32 v[32:33], v[32:33], v[88:89] op_sel_hi:[1,0]
	v_pk_mul_f32 v[30:31], v[30:31], v[88:89] op_sel_hi:[1,0]
	s_waitcnt vmcnt(15)
; #define GAS __attribute__((address_space(1)))
; DI unsigned pk2(float a, float b) { f32x2 v = {a, b}; bf16x2_t r = __builtin_convertvector(v, bf16x2_t); return __builtin_bit_cast(unsigned, r); }
; template <bool LAT_BF16>
; DI void modulate_phase(const float* xlat, const float* xctx, const float* g, const float* mods_l, bf16_t* h, int tid) {
;     ...
; #pragma unroll
;         for (int q = 0; q < 2; ++q) {
;             float ss = 0.f;
; #pragma unroll
;             for (int j = 0; j < 4; ++j) ss += (v[q][j].x * v[q][j].x + v[q][j].y * v[q][j].y) + (v[q][j].z * v[q][j].z + v[q][j].w * v[q][j].w);
;             const float rstd = 1.f / sqrtf(wave_sum(ss) * (1.f / D) + EPS);
;             if (ok[q]) {
; #pragma unroll
;                 for (int j = 0; j < 4; ++j) {
;                     const int k = lane * 4 + 256 * j;
;                     const f32x4 gg = *(const GAS f32x4*)(g + k), sh = *(const GAS f32x4*)(md[q] + k), sc = *(const GAS f32x4*)(md[q] + 1024 + k);
;                     const f32x4 o = (v[q][j] * rstd * gg) * (sc + 1.f) + sh;
;                     u32x2 w; w.x = pk2(o.x, o.y); w.y = pk2(o.z, o.w);
;                     *(GAS u32x2*)(h + (size_t)row[q] * D + k) = w;
;                 }
;             }
	v_pk_mul_f32 v[32:33], v[74:75], v[32:33]
	v_pk_mul_f32 v[30:31], v[72:73], v[30:31]
	s_waitcnt vmcnt(13)
	v_pk_add_f32 v[72:73], v[82:83], 1.0 op_sel_hi:[1,0]
	v_pk_add_f32 v[74:75], v[80:81], 1.0 op_sel_hi:[1,0]
	v_pk_fma_f32 v[32:33], v[72:73], v[32:33], v[78:79]
	v_pk_fma_f32 v[30:31], v[74:75], v[30:31], v[76:77]
	v_pk_mul_f32 v[28:29], v[28:29], v[88:89] op_sel_hi:[1,0]
	v_cvt_pk_bf16_f32 v30, v30, v31
	v_cvt_pk_bf16_f32 v31, v32, v33
	global_store_dwordx2 v[54:55], v[30:31], off
	v_lshlrev_b32_e32 v30, 2, v42
	v_mov_b32_e32 v31, v39
	v_lshl_add_u64 v[32:33], v[84:85], 0, v[30:31]
	v_pk_mul_f32 v[26:27], v[26:27], v[88:89] op_sel_hi:[1,0]
	v_lshlrev_b32_e32 v32, 2, v44
	v_mov_b32_e32 v33, v39
	v_pk_mul_f32 v[24:25], v[24:25], v[88:89] op_sel_hi:[1,0]
	v_pk_mul_f32 v[22:23], v[22:23], v[88:89] op_sel_hi:[1,0]
	v_pk_mul_f32 v[4:5], v[4:5], v[88:89] op_sel_hi:[1,0]
	s_waitcnt vmcnt(12)
	v_mul_f32_e32 v57, v105, v105
	v_fmac_f32_e32 v57, v104, v104
	s_waitcnt vmcnt(9)
	v_pk_mul_f32 v[26:27], v[120:121], v[26:27]
	v_pk_mul_f32 v[28:29], v[122:123], v[28:29]
	s_waitcnt vmcnt(8)
	v_pk_add_f32 v[72:73], v[130:131], 1.0 op_sel_hi:[1,0]
	v_pk_add_f32 v[74:75], v[128:129], 1.0 op_sel_hi:[1,0]
	s_waitcnt vmcnt(7)
	v_pk_fma_f32 v[28:29], v[72:73], v[28:29], v[134:135]
	v_pk_fma_f32 v[26:27], v[74:75], v[26:27], v[132:133]
	s_nop 0
	v_cvt_pk_bf16_f32 v26, v26, v27
	v_cvt_pk_bf16_f32 v27, v28, v29
	global_store_dwordx2 v[54:55], v[26:27], off offset:512
	v_lshl_add_u64 v[26:27], v[84:85], 0, v[32:33]
	v_lshlrev_b32_e32 v26, 2, v46
	v_mov_b32_e32 v27, v39
	s_waitcnt vmcnt(7)
	v_pk_mul_f32 v[22:23], v[136:137], v[22:23]
	v_pk_mul_f32 v[24:25], v[138:139], v[24:25]
	s_waitcnt vmcnt(6)
	v_pk_add_f32 v[28:29], v[146:147], 1.0 op_sel_hi:[1,0]
	v_pk_add_f32 v[72:73], v[144:145], 1.0 op_sel_hi:[1,0]
	s_waitcnt vmcnt(5)
	v_pk_fma_f32 v[24:25], v[24:25], v[28:29], v[150:151]
	v_pk_fma_f32 v[22:23], v[22:23], v[72:73], v[148:149]
	v_lshl_add_u64 v[28:29], v[84:85], 0, v[26:27]
	v_cvt_pk_bf16_f32 v22, v22, v23
	v_cvt_pk_bf16_f32 v23, v24, v25
	global_store_dwordx2 v[54:55], v[22:23], off offset:1024
	s_nop 0
	v_mul_f32_e32 v28, v101, v101
	v_mul_f32_e32 v29, v103, v103
	v_mul_f32_e32 v80, v107, v107
	v_mul_f32_e32 v81, v113, v113
	v_mul_f32_e32 v82, v115, v115
	v_fmac_f32_e32 v28, v100, v100
	v_fmac_f32_e32 v29, v102, v102
	v_fmac_f32_e32 v80, v106, v106
	v_mul_f32_e32 v83, v117, v117
	v_mul_f32_e32 v84, v119, v119
	v_fmac_f32_e32 v81, v112, v112
	v_fmac_f32_e32 v82, v114, v114
	v_add_f32_e32 v28, v28, v29
	v_add_f32_e32 v29, v57, v80
	v_fmac_f32_e32 v83, v116, v116
	v_fmac_f32_e32 v84, v118, v118
	v_add_f32_e32 v57, v81, v82
	v_add_f32_e32 v28, v28, v29
	v_add_f32_e32 v80, v83, v84
	v_add_f32_e32 v28, v28, v57
	v_add_f32_e32 v28, v28, v80
	ds_bpermute_b32 v29, v65, v28
	s_waitcnt lgkmcnt(0)
	v_add_f32_e32 v28, v28, v29
	ds_bpermute_b32 v29, v66, v28
	s_waitcnt lgkmcnt(0)
	v_add_f32_e32 v28, v28, v29
	ds_bpermute_b32 v29, v67, v28
	s_waitcnt lgkmcnt(0)
	v_add_f32_e32 v28, v28, v29
	ds_bpermute_b32 v29, v68, v28
	s_waitcnt lgkmcnt(0)
	v_add_f32_e32 v57, v28, v29
	ds_bpermute_b32 v80, v69, v57
	v_pk_mul_f32 v[28:29], v[2:3], v[88:89] op_sel_hi:[1,0]
	s_waitcnt lgkmcnt(0)
	v_add_f32_e32 v2, v57, v80
	ds_bpermute_b32 v3, v70, v2
	s_waitcnt vmcnt(5)
	v_pk_mul_f32 v[22:23], v[28:29], v[152:153]
	v_pk_mul_f32 v[4:5], v[4:5], v[154:155]
	s_waitcnt vmcnt(4)
	v_pk_add_f32 v[24:25], v[162:163], 1.0 op_sel_hi:[1,0]
	v_pk_add_f32 v[28:29], v[160:161], 1.0 op_sel_hi:[1,0]
	s_waitcnt vmcnt(3)
	v_pk_fma_f32 v[4:5], v[4:5], v[24:25], v[166:167]
	v_pk_fma_f32 v[22:23], v[22:23], v[28:29], v[164:165]
	s_nop 0
	v_cvt_pk_bf16_f32 v22, v22, v23
	v_cvt_pk_bf16_f32 v23, v4, v5
	global_store_dwordx2 v[54:55], v[22:23], off offset:1536
	s_and_saveexec_b64 s[8:9], s[6:7]
	s_cbranch_execz .LBB0_128
; #define GAS __attribute__((address_space(1)))
; DI unsigned pk2(float a, float b) { f32x2 v = {a, b}; bf16x2_t r = __builtin_convertvector(v, bf16x2_t); return __builtin_bit_cast(unsigned, r); }
; template <bool LAT_BF16>
; DI void modulate_phase(const float* xlat, const float* xctx, const float* g, const float* mods_l, bf16_t* h, int tid) {
;     ...
; #pragma unroll
;         for (int q = 0; q < 2; ++q) {
;             float ss = 0.f;
; #pragma unroll
;             for (int j = 0; j < 4; ++j) ss += (v[q][j].x * v[q][j].x + v[q][j].y * v[q][j].y) + (v[q][j].z * v[q][j].z + v[q][j].w * v[q][j].w);
;             const float rstd = 1.f / sqrtf(wave_sum(ss) * (1.f / D) + EPS);
;             if (ok[q]) {
; #pragma unroll
;                 for (int j = 0; j < 4; ++j) {
;                     const int k = lane * 4 + 256 * j;
;                     const f32x4 gg = *(const GAS f32x4*)(g + k), sh = *(const GAS f32x4*)(md[q] + k), sc = *(const GAS f32x4*)(md[q] + 1024 + k);
;                     const f32x4 o = (v[q][j] * rstd * gg) * (sc + 1.f) + sh;
;                     u32x2 w; w.x = pk2(o.x, o.y); w.y = pk2(o.z, o.w);
;                     *(GAS u32x2*)(h + (size_t)row[q] * D + k) = w;
;                 }
;             }
	v_lshl_add_u64 v[28:29], v[58:59], 0, s[44:45]
	v_lshl_add_u64 v[4:5], v[28:29], 0, v[38:39]
	global_load_dwordx4 v[22:25], v[40:41], off
	global_load_dwordx4 v[72:75], v[4:5], off
	v_lshl_add_u64 v[58:59], v[58:59], 0, v[38:39]
	global_load_dwordx4 v[76:79], v[58:59], off
	global_load_dwordx4 v[168:171], v[40:41], off offset:1024
	v_lshl_add_u64 v[172:173], v[28:29], 0, v[30:31]
	global_load_dwordx4 v[176:179], v[172:173], off
	global_load_dwordx4 v[180:183], v[58:59], off offset:1024
	global_load_dwordx4 v[184:187], v[40:41], off offset:2048
	v_lshl_add_u64 v[174:175], v[28:29], 0, v[32:33]
	global_load_dwordx4 v[188:191], v[174:175], off
	global_load_dwordx4 v[192:195], v[58:59], off offset:2048
	global_load_dwordx4 v[196:199], v[40:41], off offset:3072
	v_lshl_add_u64 v[204:205], v[28:29], 0, v[26:27]
	global_load_dwordx4 v[208:211], v[204:205], off
	global_load_dwordx4 v[212:215], v[58:59], off offset:3072
	s_waitcnt lgkmcnt(0)
	v_add_f32_e32 v2, v2, v3
	v_fmamk_f32 v2, v2, 0x3a800000, v35
	v_mul_f32_e32 v3, 0x4f800000, v2
	v_cmp_gt_f32_e32 vcc, s19, v2
	v_ashrrev_i32_e32 v57, 31, v56
	s_nop 0
	v_cndmask_b32_e32 v4, v2, v3, vcc
	v_sqrt_f32_e32 v5, v4
	v_lshlrev_b64 v[2:3], 11, v[56:57]
	v_add_u32_e32 v38, -1, v5
	v_add_u32_e32 v56, 1, v5
	v_fma_f32 v57, -v38, v5, v4
	v_fma_f32 v80, -v56, v5, v4
	v_cmp_ge_f32_e64 s[6:7], 0, v57
	s_nop 1
	v_cndmask_b32_e64 v5, v5, v38, s[6:7]
	v_cmp_lt_f32_e64 s[6:7], 0, v80
	s_nop 1
	v_cndmask_b32_e64 v5, v5, v56, s[6:7]
	v_mul_f32_e32 v38, 0x37800000, v5
	v_cndmask_b32_e32 v5, v5, v38, vcc
	v_cmp_class_f32_e32 vcc, v4, v37
	v_lshl_add_u64 v[56:57], v[48:49], 0, v[2:3]
	s_nop 0
	v_cndmask_b32_e32 v4, v5, v4, vcc
	v_div_scale_f32 v5, s[6:7], v4, v4, 1.0
	v_rcp_f32_e32 v38, v5
	v_div_scale_f32 v2, vcc, 1.0, v4, 1.0
	v_fma_f32 v3, -v5, v38, 1.0
	v_fmac_f32_e32 v38, v3, v38
	v_mul_f32_e32 v3, v2, v38
	v_fma_f32 v80, -v5, v3, v2
	v_fmac_f32_e32 v3, v80, v38
	v_fma_f32 v2, -v5, v3, v2
	v_div_fmas_f32 v2, v2, v38, v3
	v_div_fixup_f32 v38, v2, v4, 1.0
	v_pk_mul_f32 v[2:3], v[102:103], v[38:39] op_sel_hi:[1,0]
	v_pk_mul_f32 v[4:5], v[100:101], v[38:39] op_sel_hi:[1,0]
	v_pk_mul_f32 v[16:17], v[106:107], v[38:39] op_sel_hi:[1,0]
	v_pk_mul_f32 v[14:15], v[104:105], v[38:39] op_sel_hi:[1,0]
	v_pk_mul_f32 v[12:13], v[114:115], v[38:39] op_sel_hi:[1,0]
	v_pk_mul_f32 v[10:11], v[112:113], v[38:39] op_sel_hi:[1,0]
	v_pk_mul_f32 v[8:9], v[118:119], v[38:39] op_sel_hi:[1,0]
	v_pk_mul_f32 v[6:7], v[116:117], v[38:39] op_sel_hi:[1,0]
	s_waitcnt vmcnt(11)
	v_pk_mul_f32 v[4:5], v[4:5], v[22:23]
	v_pk_mul_f32 v[2:3], v[2:3], v[24:25]
	s_waitcnt vmcnt(10)
	v_pk_add_f32 v[18:19], v[74:75], 1.0 op_sel_hi:[1,0]
	v_pk_add_f32 v[20:21], v[72:73], 1.0 op_sel_hi:[1,0]
	s_waitcnt vmcnt(9)
	v_pk_fma_f32 v[2:3], v[2:3], v[18:19], v[78:79]
	v_pk_fma_f32 v[4:5], v[4:5], v[20:21], v[76:77]
	v_lshl_add_u64 v[18:19], v[28:29], 0, v[30:31]
	v_cvt_pk_bf16_f32 v4, v4, v5
	v_cvt_pk_bf16_f32 v5, v2, v3
	global_store_dwordx2 v[56:57], v[4:5], off
	s_nop 0
	s_nop 0
	s_waitcnt vmcnt(9)
	v_pk_mul_f32 v[2:3], v[14:15], v[168:169]
	v_pk_mul_f32 v[4:5], v[16:17], v[170:171]
	s_waitcnt vmcnt(8)
	v_pk_add_f32 v[14:15], v[178:179], 1.0 op_sel_hi:[1,0]
	v_pk_add_f32 v[16:17], v[176:177], 1.0 op_sel_hi:[1,0]
	s_waitcnt vmcnt(7)
	v_pk_fma_f32 v[4:5], v[4:5], v[14:15], v[182:183]
	v_pk_fma_f32 v[2:3], v[2:3], v[16:17], v[180:181]
	v_lshl_add_u64 v[14:15], v[28:29], 0, v[32:33]
	v_cvt_pk_bf16_f32 v2, v2, v3
	v_cvt_pk_bf16_f32 v3, v4, v5
	global_store_dwordx2 v[56:57], v[2:3], off offset:512
	s_nop 0
	s_nop 0
	s_waitcnt vmcnt(7)
	v_pk_mul_f32 v[2:3], v[10:11], v[184:185]
	v_pk_mul_f32 v[4:5], v[12:13], v[186:187]
	s_waitcnt vmcnt(6)
	v_pk_add_f32 v[10:11], v[190:191], 1.0 op_sel_hi:[1,0]
	v_pk_add_f32 v[12:13], v[188:189], 1.0 op_sel_hi:[1,0]
	s_waitcnt vmcnt(5)
	v_pk_fma_f32 v[4:5], v[4:5], v[10:11], v[194:195]
	v_pk_fma_f32 v[2:3], v[2:3], v[12:13], v[192:193]
	v_lshl_add_u64 v[10:11], v[28:29], 0, v[26:27]
	v_cvt_pk_bf16_f32 v2, v2, v3
	v_cvt_pk_bf16_f32 v3, v4, v5
	global_store_dwordx2 v[56:57], v[2:3], off offset:1024
	s_nop 0
	s_nop 0
	s_waitcnt vmcnt(5)
	v_pk_mul_f32 v[2:3], v[6:7], v[196:197]
	v_pk_mul_f32 v[4:5], v[8:9], v[198:199]
	s_waitcnt vmcnt(4)
	v_pk_add_f32 v[6:7], v[210:211], 1.0 op_sel_hi:[1,0]
	v_pk_add_f32 v[8:9], v[208:209], 1.0 op_sel_hi:[1,0]
	s_waitcnt vmcnt(3)
	v_pk_fma_f32 v[4:5], v[4:5], v[6:7], v[214:215]
	v_pk_fma_f32 v[2:3], v[2:3], v[8:9], v[212:213]
	s_nop 0
	v_cvt_pk_bf16_f32 v2, v2, v3
	v_cvt_pk_bf16_f32 v3, v4, v5
	global_store_dwordx2 v[56:57], v[2:3], off offset:1536
	s_branch .LBB0_128
